# P10: every thread touches one of the unit's 256 row-norm partial rows during the last K iteration so the epilogue loads hit L2
# baseline (speedup 1.0000x reference)
.LBB0_1360:
	s_cmp_lg_u32 s53, 14
	s_cbranch_scc1 .Lp10_nopf
	v_mov_b32_e32 v250, s26
	v_and_b32_e32 v251, 0xff, v0
	v_lshl_add_u32 v250, v250, 8, v251
	v_mov_b32_e32 v251, 0
	v_lshlrev_b64 v[250:251], 6, v[250:251]
	v_lshl_add_u64 v[250:251], s[12:13], 0, v[250:251]
	global_load_dword v252, v[250:251], off
